# all GEMM epilogues (hand-written and the remaining original side-output path) drain their stores before the wave can reach the grid barrier
# baseline (speedup 1.0000x reference)
.LBB0_1416:
	s_or_b64 exec, exec, s[8:9]
	s_movk_i32 s96, 0x1000
	s_movk_i32 s97, 0x2000
	s_waitcnt vmcnt(0)
	s_branch .LBB0_1041
